# drop XNACK padding s_nop between back-to-back staging loads in both SSD loops (45 nops)
# speedup vs baseline: 1.0029x; 1.0029x over previous
.Lmy_pdt_a:
	s_or_b64 exec, exec, s[100:101]
	s_xor_b64 s[24:25], s[22:23], -1
	s_xor_b64 s[22:23], s[78:79], -1
	s_add_i32 s47, s47, 1
	s_cmp_eq_u32 s35, 0
	s_cselect_b64 s[78:79], -1, 0
	s_andn2_b64 vcc, exec, s[24:25]
	s_mov_b64 s[24:25], -1
	s_cbranch_vccnz .LBB0_1113
	s_and_b64 s[24:25], s[78:79], exec
	s_mov_b32 s24, 0x1e400
	s_cselect_b32 s24, 0x1a000, s24
	v_add_u32_e32 v94, s24, v149
	s_nop 0
	ds_read_b128 v[66:69], v94
	ds_read_b128 v[98:101], v161
	ds_read_b128 v[70:73], v94 offset:4352
	ds_read_b128 v[74:77], v94 offset:8704
	ds_read_b128 v[82:85], v94 offset:64
	ds_read_b128 v[102:105], v161 offset:64
	s_waitcnt lgkmcnt(4)
	v_mfma_f32_16x16x32_bf16 v[66:69], v[66:69], v[98:101], 0
	ds_read_b128 v[78:81], v94 offset:13056
	s_andn2_b64 vcc, exec, s[62:63]
	s_waitcnt lgkmcnt(4)
	v_mfma_f32_16x16x32_bf16 v[70:73], v[70:73], v[98:101], 0
	s_waitcnt lgkmcnt(1)
	v_mfma_f32_16x16x32_bf16 v[66:69], v[82:85], v[102:105], v[66:69]
	ds_read_b128 v[82:85], v94 offset:4416
	v_mfma_f32_16x16x32_bf16 v[74:77], v[74:77], v[98:101], 0
	s_waitcnt lgkmcnt(0)
	v_mfma_f32_16x16x32_bf16 v[70:73], v[82:85], v[102:105], v[70:73]
	ds_read_b128 v[82:85], v94 offset:8768
	v_mfma_f32_16x16x32_bf16 v[78:81], v[78:81], v[98:101], 0
	s_waitcnt lgkmcnt(0)
	v_mfma_f32_16x16x32_bf16 v[74:77], v[82:85], v[102:105], v[74:77]
	ds_read_b128 v[82:85], v94 offset:13120
	ds_read_b128 v[86:89], v94 offset:128
	s_waitcnt lgkmcnt(1)
	v_mfma_f32_16x16x32_bf16 v[78:81], v[82:85], v[102:105], v[78:81]
	ds_read_b128 v[106:109], v161 offset:128
	ds_read_b128 v[82:85], v94 offset:4480
	s_waitcnt lgkmcnt(1)
	v_mfma_f32_16x16x32_bf16 v[66:69], v[86:89], v[106:109], v[66:69]
	ds_read_b128 v[86:89], v94 offset:8832
	s_waitcnt lgkmcnt(1)
	v_mfma_f32_16x16x32_bf16 v[70:73], v[82:85], v[106:109], v[70:73]
	ds_read_b128 v[82:85], v94 offset:13184
	s_waitcnt lgkmcnt(1)
	v_mfma_f32_16x16x32_bf16 v[74:77], v[86:89], v[106:109], v[74:77]
	ds_read_b128 v[86:89], v94 offset:192
	ds_read_b128 v[90:93], v94 offset:4544
	ds_read_b128 v[110:113], v161 offset:192
	s_waitcnt lgkmcnt(3)
	v_mfma_f32_16x16x32_bf16 v[82:85], v[82:85], v[106:109], v[78:81]
	s_waitcnt lgkmcnt(0)
	v_mfma_f32_16x16x32_bf16 v[66:69], v[86:89], v[110:113], v[66:69]
	s_nop 0
	ds_read_b128 v[78:81], v94 offset:8896
	ds_read_b128 v[86:89], v94 offset:13248
	v_mfma_f32_16x16x32_bf16 v[70:73], v[90:93], v[110:113], v[70:73]
	s_waitcnt lgkmcnt(1)
	v_mfma_f32_16x16x32_bf16 v[78:81], v[78:81], v[110:113], v[74:77]
	s_waitcnt lgkmcnt(0)
	v_mfma_f32_16x16x32_bf16 v[74:77], v[86:89], v[110:113], v[82:85]
	s_cbranch_vccnz .LBB0_1043
	s_and_b64 s[24:25], s[92:93], exec
	s_cselect_b32 s24, 1, 35
	s_sub_i32 s24, s24, s47
	s_lshl_b32 s25, s24, 7
	s_or_b32 s26, s25, s0
	s_add_i32 s25, s25, s1
	s_cmp_lt_u32 s24, 2
	s_cselect_b32 s24, s26, s25
	v_add_u32_e32 v0, s24, v137
	v_ashrrev_i32_e32 v1, 31, v0
	v_lshlrev_b64 v[0:1], 13, v[0:1]
	v_add_u32_e32 v8, s24, v138
	v_lshl_add_u64 v[0:1], s[44:45], 0, v[0:1]
	s_mov_b32 s83, s67
	v_ashrrev_i32_e32 v9, 31, v8
	v_lshl_add_u64 v[0:1], v[0:1], 0, s[82:83]
	v_lshlrev_b64 v[8:9], 13, v[8:9]
	v_add_u32_e32 v16, s24, v139
	v_lshl_add_u64 v[0:1], v[0:1], 0, v[64:65]
	s_movk_i32 s25, 0x1000
	v_lshl_add_u64 v[8:9], s[44:45], 0, v[8:9]
	v_ashrrev_i32_e32 v17, 31, v16
	v_add_co_u32_e32 v4, vcc, s25, v0
	v_lshl_add_u64 v[8:9], v[8:9], 0, s[82:83]
	v_lshlrev_b64 v[16:17], 13, v[16:17]
	v_add_u32_e32 v24, s24, v140
	v_addc_co_u32_e32 v5, vcc, 0, v1, vcc
	v_lshl_add_u64 v[8:9], v[8:9], 0, v[64:65]
	v_lshl_add_u64 v[16:17], s[44:45], 0, v[16:17]
	v_ashrrev_i32_e32 v25, 31, v24
	v_add_co_u32_e32 v12, vcc, s25, v8
	v_lshl_add_u64 v[16:17], v[16:17], 0, s[82:83]
	v_lshlrev_b64 v[24:25], 13, v[24:25]
	v_addc_co_u32_e32 v13, vcc, 0, v9, vcc
	v_lshl_add_u64 v[16:17], v[16:17], 0, v[64:65]
	v_lshl_add_u64 v[24:25], s[44:45], 0, v[24:25]
	v_add_co_u32_e32 v20, vcc, s25, v16
	v_lshl_add_u64 v[24:25], v[24:25], 0, s[82:83]
	v_add_u32_e32 v32, s24, v136
	v_addc_co_u32_e32 v21, vcc, 0, v17, vcc
	v_lshl_add_u64 v[24:25], v[24:25], 0, v[64:65]
	v_ashrrev_i32_e32 v33, 31, v32
	v_add_co_u32_e32 v28, vcc, s25, v24
	v_lshlrev_b64 v[32:33], 13, v[32:33]
	s_nop 0
	v_addc_co_u32_e32 v29, vcc, 0, v25, vcc
	v_lshl_add_u64 v[36:37], v[130:131], 0, v[32:33]
	global_load_dwordx4 v[0:3], v[4:5], off offset:2048
	global_load_dwordx4 v[4:7], v[4:5], off
	global_load_dwordx4 v[8:11], v[12:13], off offset:2048
	global_load_dwordx4 v[12:15], v[12:13], off
	global_load_dwordx4 v[16:19], v[20:21], off offset:2048
	global_load_dwordx4 v[20:23], v[20:21], off
	global_load_dwordx4 v[24:27], v[28:29], off offset:2048
	global_load_dwordx4 v[28:31], v[28:29], off
	global_load_dwordx4 v[32:35], v[36:37], off offset:16
	global_load_dwordx4 v[36:39], v[36:37], off
	s_mov_b32 s83, 0x41a00000

.LBB0_1113:
	s_and_b64 vcc, exec, s[24:25]
	s_cbranch_vccz .LBB0_1009
	s_and_b64 s[22:23], s[92:93], exec
	s_cselect_b32 s22, 1, 35
	s_sub_i32 s22, s22, s47
	s_lshl_b32 s23, s22, 7
	s_or_b32 s24, s23, s0
	s_add_i32 s23, s23, s1
	s_cmp_lt_u32 s22, 2
	s_cselect_b32 s22, s24, s23
	v_add_u32_e32 v0, s22, v137
	v_ashrrev_i32_e32 v1, 31, v0
	v_lshlrev_b64 v[0:1], 13, v[0:1]
	v_add_u32_e32 v8, s22, v138
	v_lshl_add_u64 v[0:1], s[44:45], 0, v[0:1]
	s_mov_b32 s83, s67
	v_ashrrev_i32_e32 v9, 31, v8
	v_lshl_add_u64 v[0:1], v[0:1], 0, s[82:83]
	v_lshlrev_b64 v[8:9], 13, v[8:9]
	v_add_u32_e32 v16, s22, v139
	v_lshl_add_u64 v[0:1], v[0:1], 0, v[64:65]
	s_movk_i32 s23, 0x1000
	v_lshl_add_u64 v[8:9], s[44:45], 0, v[8:9]
	v_ashrrev_i32_e32 v17, 31, v16
	v_add_co_u32_e32 v4, vcc, s23, v0
	v_lshl_add_u64 v[8:9], v[8:9], 0, s[82:83]
	v_lshlrev_b64 v[16:17], 13, v[16:17]
	v_add_u32_e32 v24, s22, v140
	v_addc_co_u32_e32 v5, vcc, 0, v1, vcc
	v_lshl_add_u64 v[8:9], v[8:9], 0, v[64:65]
	v_lshl_add_u64 v[16:17], s[44:45], 0, v[16:17]
	v_ashrrev_i32_e32 v25, 31, v24
	v_add_co_u32_e32 v12, vcc, s23, v8
	v_lshl_add_u64 v[16:17], v[16:17], 0, s[82:83]
	v_lshlrev_b64 v[24:25], 13, v[24:25]
	v_addc_co_u32_e32 v13, vcc, 0, v9, vcc
	v_lshl_add_u64 v[16:17], v[16:17], 0, v[64:65]
	v_lshl_add_u64 v[24:25], s[44:45], 0, v[24:25]
	v_add_co_u32_e32 v20, vcc, s23, v16
	v_lshl_add_u64 v[24:25], v[24:25], 0, s[82:83]
	v_add_u32_e32 v32, s22, v136
	v_addc_co_u32_e32 v21, vcc, 0, v17, vcc
	v_lshl_add_u64 v[24:25], v[24:25], 0, v[64:65]
	v_ashrrev_i32_e32 v33, 31, v32
	v_add_co_u32_e32 v28, vcc, s23, v24
	v_lshlrev_b64 v[32:33], 13, v[32:33]
	s_nop 0
	v_addc_co_u32_e32 v29, vcc, 0, v25, vcc
	v_lshl_add_u64 v[36:37], v[130:131], 0, v[32:33]
	global_load_dwordx4 v[0:3], v[4:5], off offset:2048
	global_load_dwordx4 v[4:7], v[4:5], off
	global_load_dwordx4 v[8:11], v[12:13], off offset:2048
	global_load_dwordx4 v[12:15], v[12:13], off
	global_load_dwordx4 v[16:19], v[20:21], off offset:2048
	global_load_dwordx4 v[20:23], v[20:21], off
	global_load_dwordx4 v[24:27], v[28:29], off offset:2048
	global_load_dwordx4 v[28:31], v[28:29], off
	global_load_dwordx4 v[32:35], v[36:37], off offset:16
	global_load_dwordx4 v[36:39], v[36:37], off
	s_mov_b32 s83, 0x41a00000
	s_mov_b32 s26, s66
	s_branch .LBB0_1009

.LBB0_1125:
	s_add_u32 s44, s12, 0x8ac0000
	s_addc_u32 s45, s13, 0
	s_add_u32 s14, s12, 0x4280000
	s_addc_u32 s15, s13, 0
	s_ashr_i32 s31, s6, 6
	s_lshl_b32 s10, s31, 8
	s_add_i32 s4, s10, 0x4000
	v_lshlrev_b32_e32 v0, 3, v42
	v_ashrrev_i32_e32 v139, 4, v42
	v_and_b32_e32 v2, 0x78, v0
	v_add_u32_e32 v0, s4, v139
	v_add_u32_e32 v8, 0x200, v42
	s_lshl_b32 s2, s1, 5
	v_ashrrev_i32_e32 v1, 31, v0
	v_ashrrev_i32_e32 v140, 4, v8
	s_and_b32 s2, s2, 0x380
	v_lshlrev_b64 v[0:1], 13, v[0:1]
	v_add_u32_e32 v8, s4, v140
	v_add_u32_e32 v16, 0x400, v42
	v_lshl_add_u64 v[0:1], s[44:45], 0, v[0:1]
	s_lshl_b32 s82, s2, 1
	s_mov_b32 s83, s67
	v_ashrrev_i32_e32 v9, 31, v8
	v_ashrrev_i32_e32 v141, 4, v16
	v_lshlrev_b32_e32 v64, 1, v2
	v_lshl_add_u64 v[0:1], v[0:1], 0, s[82:83]
	v_lshlrev_b64 v[8:9], 13, v[8:9]
	v_add_u32_e32 v16, s4, v141
	v_add_u32_e32 v24, 0x600, v42
	v_lshl_add_u64 v[0:1], v[0:1], 0, v[64:65]
	s_movk_i32 s2, 0x1000
	v_lshl_add_u64 v[8:9], s[44:45], 0, v[8:9]
	v_ashrrev_i32_e32 v17, 31, v16
	v_ashrrev_i32_e32 v142, 4, v24
	v_add_co_u32_e32 v4, vcc, s2, v0
	v_lshl_add_u64 v[8:9], v[8:9], 0, s[82:83]
	v_lshlrev_b64 v[16:17], 13, v[16:17]
	v_add_u32_e32 v24, s4, v142
	v_ashrrev_i32_e32 v138, 2, v42
	v_addc_co_u32_e32 v5, vcc, 0, v1, vcc
	v_lshl_add_u64 v[8:9], v[8:9], 0, v[64:65]
	v_lshl_add_u64 v[16:17], s[44:45], 0, v[16:17]
	v_ashrrev_i32_e32 v25, 31, v24
	v_add_co_u32_e32 v12, vcc, s2, v8
	v_lshl_add_u64 v[16:17], v[16:17], 0, s[82:83]
	v_lshlrev_b64 v[24:25], 13, v[24:25]
	v_add_u32_e32 v32, s4, v138
	v_addc_co_u32_e32 v13, vcc, 0, v9, vcc
	v_lshl_add_u64 v[16:17], v[16:17], 0, v[64:65]
	v_lshl_add_u64 v[24:25], s[44:45], 0, v[24:25]
	v_ashrrev_i32_e32 v33, 31, v32
	v_add_co_u32_e32 v20, vcc, s2, v16
	v_lshl_add_u64 v[24:25], v[24:25], 0, s[82:83]
	v_lshlrev_b64 v[32:33], 13, v[32:33]
	v_and_b32_e32 v48, 3, v42
	v_addc_co_u32_e32 v21, vcc, 0, v17, vcc
	v_lshl_add_u64 v[24:25], v[24:25], 0, v[64:65]
	v_lshl_add_u64 v[32:33], s[44:45], 0, v[32:33]
	s_lshl_b32 s66, s1, 7
	v_add_co_u32_e32 v28, vcc, s2, v24
	v_lshl_add_u64 v[32:33], v[32:33], 0, s[66:67]
	v_lshlrev_b32_e32 v34, 5, v48
	v_mov_b32_e32 v35, v65
	v_addc_co_u32_e32 v29, vcc, 0, v25, vcc
	v_lshl_add_u64 v[36:37], v[32:33], 0, v[34:35]
	global_load_dwordx4 v[0:3], v[4:5], off offset:2048
	global_load_dwordx4 v[4:7], v[4:5], off
	global_load_dwordx4 v[8:11], v[12:13], off offset:2048
	global_load_dwordx4 v[12:15], v[12:13], off
	global_load_dwordx4 v[16:19], v[20:21], off offset:2048
	global_load_dwordx4 v[20:23], v[20:21], off
	global_load_dwordx4 v[24:27], v[28:29], off offset:2048
	global_load_dwordx4 v[28:31], v[28:29], off
	global_load_dwordx4 v[32:35], v[36:37], off offset:16
	global_load_dwordx4 v[36:39], v[36:37], off
	s_movk_i32 s2, 0x7f
	v_cmp_lt_u32_e32 vcc, s2, v42
	s_movk_i32 s2, 0x80
	v_cmp_gt_u32_e64 s[2:3], s2, v42
	s_mul_i32 s66, s1, 0x11000
	s_and_saveexec_b64 s[6:7], s[2:3]
	s_cbranch_execz .LBB0_1127
	s_ashr_i32 s5, s4, 31
	s_add_u32 s8, s14, s66
	s_addc_u32 s9, s15, 0
	s_lshl_b64 s[4:5], s[4:5], 2
	s_add_u32 s4, s8, s4
	v_mov_b32_e32 v43, v65
	s_addc_u32 s5, s9, s5
	v_lshl_add_u64 v[46:47], v[42:43], 2, s[4:5]
	global_load_dword v40, v[46:47], off
	v_lshl_add_u32 v43, v42, 2, 0
	v_add_u32_e32 v43, 0x23000, v43
	s_waitcnt vmcnt(0)
	ds_write_b32 v43, v40

.Lmy_pdt_b:
	s_or_b64 exec, exec, s[100:101]
	s_xor_b64 s[24:25], s[22:23], -1
	s_xor_b64 s[36:37], s[36:37], -1
	s_add_i32 s26, s34, 1
	s_cmp_eq_u32 s83, 0
	s_cselect_b64 s[22:23], -1, 0
	s_andn2_b64 vcc, exec, s[24:25]
	s_mov_b64 s[24:25], -1
	s_cbranch_vccnz .LBB0_1235
	s_and_b64 s[24:25], s[22:23], exec
	s_mov_b32 s24, 0x1e400
	s_cselect_b32 s24, 0x1a000, s24
	v_add_u32_e32 v94, s24, v151
	s_nop 0
	ds_read_b128 v[66:69], v94
	ds_read_b128 v[102:105], v161
	ds_read_b128 v[70:73], v94 offset:4352
	ds_read_b128 v[74:77], v94 offset:8704
	ds_read_b128 v[82:85], v94 offset:64
	ds_read_b128 v[106:109], v161 offset:64
	s_waitcnt lgkmcnt(4)
	v_mfma_f32_16x16x32_bf16 v[66:69], v[66:69], v[102:105], 0
	ds_read_b128 v[78:81], v94 offset:13056
	s_andn2_b64 vcc, exec, s[20:21]
	s_waitcnt lgkmcnt(4)
	v_mfma_f32_16x16x32_bf16 v[70:73], v[70:73], v[102:105], 0
	s_waitcnt lgkmcnt(1)
	v_mfma_f32_16x16x32_bf16 v[66:69], v[82:85], v[106:109], v[66:69]
	ds_read_b128 v[82:85], v94 offset:4416
	v_mfma_f32_16x16x32_bf16 v[74:77], v[74:77], v[102:105], 0
	s_waitcnt lgkmcnt(0)
	v_mfma_f32_16x16x32_bf16 v[70:73], v[82:85], v[106:109], v[70:73]
	ds_read_b128 v[82:85], v94 offset:8768
	v_mfma_f32_16x16x32_bf16 v[78:81], v[78:81], v[102:105], 0
	s_waitcnt lgkmcnt(0)
	v_mfma_f32_16x16x32_bf16 v[74:77], v[82:85], v[106:109], v[74:77]
	ds_read_b128 v[82:85], v94 offset:13120
	ds_read_b128 v[86:89], v94 offset:128
	s_waitcnt lgkmcnt(1)
	v_mfma_f32_16x16x32_bf16 v[78:81], v[82:85], v[106:109], v[78:81]
	ds_read_b128 v[110:113], v161 offset:128
	ds_read_b128 v[82:85], v94 offset:4480
	s_waitcnt lgkmcnt(1)
	v_mfma_f32_16x16x32_bf16 v[66:69], v[86:89], v[110:113], v[66:69]
	ds_read_b128 v[86:89], v94 offset:8832
	s_waitcnt lgkmcnt(1)
	v_mfma_f32_16x16x32_bf16 v[70:73], v[82:85], v[110:113], v[70:73]
	ds_read_b128 v[82:85], v94 offset:13184
	s_waitcnt lgkmcnt(1)
	v_mfma_f32_16x16x32_bf16 v[86:89], v[86:89], v[110:113], v[74:77]
	s_nop 2
	ds_read_b128 v[74:77], v94 offset:192
	ds_read_b128 v[90:93], v94 offset:4544
	ds_read_b128 v[126:129], v161 offset:192
	s_waitcnt lgkmcnt(3)
	v_mfma_f32_16x16x32_bf16 v[82:85], v[82:85], v[110:113], v[78:81]
	s_waitcnt lgkmcnt(0)
	v_mfma_f32_16x16x32_bf16 v[78:81], v[74:77], v[126:129], v[66:69]
	s_nop 2
	ds_read_b128 v[66:69], v94 offset:8896
	v_mfma_f32_16x16x32_bf16 v[74:77], v[90:93], v[126:129], v[70:73]
	ds_read_b128 v[90:93], v94 offset:13248
	s_waitcnt lgkmcnt(1)
	v_mfma_f32_16x16x32_bf16 v[70:73], v[66:69], v[126:129], v[86:89]
	s_waitcnt lgkmcnt(0)
	v_mfma_f32_16x16x32_bf16 v[66:69], v[90:93], v[126:129], v[82:85]
	s_cbranch_vccnz .LBB0_1165
	s_lshl_b32 s24, s26, 7
	s_and_b64 s[20:21], s[56:57], exec
	s_movk_i32 s21, 0xff00
	s_cselect_b32 s20, 8, 12
	s_cselect_b32 s21, 0x4000, s21
	s_lshl_b32 s20, s31, s20
	s_add_i32 s21, s24, s21
	s_add_i32 s21, s21, s20
	v_add_u32_e32 v0, s21, v139
	v_ashrrev_i32_e32 v1, 31, v0
	v_lshlrev_b64 v[0:1], 13, v[0:1]
	v_add_u32_e32 v8, s21, v140
	v_lshl_add_u64 v[0:1], s[44:45], 0, v[0:1]
	s_mov_b32 s83, s67
	v_ashrrev_i32_e32 v9, 31, v8
	v_lshl_add_u64 v[0:1], v[0:1], 0, s[82:83]
	v_lshlrev_b64 v[8:9], 13, v[8:9]
	v_add_u32_e32 v16, s21, v141
	v_lshl_add_u64 v[0:1], v[0:1], 0, v[64:65]
	s_movk_i32 s20, 0x1000
	v_lshl_add_u64 v[8:9], s[44:45], 0, v[8:9]
	v_ashrrev_i32_e32 v17, 31, v16
	v_add_co_u32_e32 v4, vcc, s20, v0
	v_lshl_add_u64 v[8:9], v[8:9], 0, s[82:83]
	v_lshlrev_b64 v[16:17], 13, v[16:17]
	v_add_u32_e32 v24, s21, v142
	v_addc_co_u32_e32 v5, vcc, 0, v1, vcc
	v_lshl_add_u64 v[8:9], v[8:9], 0, v[64:65]
	v_lshl_add_u64 v[16:17], s[44:45], 0, v[16:17]
	v_ashrrev_i32_e32 v25, 31, v24
	v_add_co_u32_e32 v12, vcc, s20, v8
	v_lshl_add_u64 v[16:17], v[16:17], 0, s[82:83]
	v_lshlrev_b64 v[24:25], 13, v[24:25]
	v_addc_co_u32_e32 v13, vcc, 0, v9, vcc
	v_lshl_add_u64 v[16:17], v[16:17], 0, v[64:65]
	v_lshl_add_u64 v[24:25], s[44:45], 0, v[24:25]
	v_add_co_u32_e32 v20, vcc, s20, v16
	v_lshl_add_u64 v[24:25], v[24:25], 0, s[82:83]
	v_add_u32_e32 v32, s21, v138
	v_addc_co_u32_e32 v21, vcc, 0, v17, vcc
	v_lshl_add_u64 v[24:25], v[24:25], 0, v[64:65]
	v_ashrrev_i32_e32 v33, 31, v32
	v_add_co_u32_e32 v28, vcc, s20, v24
	v_lshlrev_b64 v[32:33], 13, v[32:33]
	s_nop 0
	v_addc_co_u32_e32 v29, vcc, 0, v25, vcc
	v_lshl_add_u64 v[36:37], v[132:133], 0, v[32:33]
	global_load_dwordx4 v[0:3], v[4:5], off offset:2048
	global_load_dwordx4 v[4:7], v[4:5], off
	global_load_dwordx4 v[8:11], v[12:13], off offset:2048
	global_load_dwordx4 v[12:15], v[12:13], off
	global_load_dwordx4 v[16:19], v[20:21], off offset:2048
	global_load_dwordx4 v[20:23], v[20:21], off
	global_load_dwordx4 v[24:27], v[28:29], off offset:2048
	global_load_dwordx4 v[28:31], v[28:29], off
	global_load_dwordx4 v[32:35], v[36:37], off offset:16
	global_load_dwordx4 v[36:39], v[36:37], off

.LBB0_1235:
	s_and_b64 vcc, exec, s[24:25]
	s_cbranch_vccz .LBB0_1237
	s_lshl_b32 s24, s26, 7
	s_and_b64 s[20:21], s[56:57], exec
	s_movk_i32 s21, 0xff00
	s_cselect_b32 s20, 8, 12
	s_cselect_b32 s21, 0x4000, s21
	s_lshl_b32 s20, s31, s20
	s_add_i32 s21, s24, s21
	s_add_i32 s21, s21, s20
	v_add_u32_e32 v0, s21, v139
	v_ashrrev_i32_e32 v1, 31, v0
	v_lshlrev_b64 v[0:1], 13, v[0:1]
	v_add_u32_e32 v8, s21, v140
	v_lshl_add_u64 v[0:1], s[44:45], 0, v[0:1]
	s_mov_b32 s83, s67
	v_ashrrev_i32_e32 v9, 31, v8
	v_lshl_add_u64 v[0:1], v[0:1], 0, s[82:83]
	v_lshlrev_b64 v[8:9], 13, v[8:9]
	v_add_u32_e32 v16, s21, v141
	v_lshl_add_u64 v[0:1], v[0:1], 0, v[64:65]
	s_movk_i32 s20, 0x1000
	v_lshl_add_u64 v[8:9], s[44:45], 0, v[8:9]
	v_ashrrev_i32_e32 v17, 31, v16
	v_add_co_u32_e32 v4, vcc, s20, v0
	v_lshl_add_u64 v[8:9], v[8:9], 0, s[82:83]
	v_lshlrev_b64 v[16:17], 13, v[16:17]
	v_add_u32_e32 v24, s21, v142
	v_addc_co_u32_e32 v5, vcc, 0, v1, vcc
	v_lshl_add_u64 v[8:9], v[8:9], 0, v[64:65]
	v_lshl_add_u64 v[16:17], s[44:45], 0, v[16:17]
	v_ashrrev_i32_e32 v25, 31, v24
	v_add_co_u32_e32 v12, vcc, s20, v8
	v_lshl_add_u64 v[16:17], v[16:17], 0, s[82:83]
	v_lshlrev_b64 v[24:25], 13, v[24:25]
	v_addc_co_u32_e32 v13, vcc, 0, v9, vcc
	v_lshl_add_u64 v[16:17], v[16:17], 0, v[64:65]
	v_lshl_add_u64 v[24:25], s[44:45], 0, v[24:25]
	v_add_co_u32_e32 v20, vcc, s20, v16
	v_lshl_add_u64 v[24:25], v[24:25], 0, s[82:83]
	v_add_u32_e32 v32, s21, v138
	v_addc_co_u32_e32 v21, vcc, 0, v17, vcc
	v_lshl_add_u64 v[24:25], v[24:25], 0, v[64:65]
	v_ashrrev_i32_e32 v33, 31, v32
	v_add_co_u32_e32 v28, vcc, s20, v24
	v_lshlrev_b64 v[32:33], 13, v[32:33]
	s_nop 0
	v_addc_co_u32_e32 v29, vcc, 0, v25, vcc
	v_lshl_add_u64 v[36:37], v[132:133], 0, v[32:33]
	global_load_dwordx4 v[0:3], v[4:5], off offset:2048
	global_load_dwordx4 v[4:7], v[4:5], off
	global_load_dwordx4 v[8:11], v[12:13], off offset:2048
	global_load_dwordx4 v[12:15], v[12:13], off
	global_load_dwordx4 v[16:19], v[20:21], off offset:2048
	global_load_dwordx4 v[20:23], v[20:21], off
	global_load_dwordx4 v[24:27], v[28:29], off offset:2048
	global_load_dwordx4 v[28:31], v[28:29], off
	global_load_dwordx4 v[32:35], v[36:37], off offset:16
	global_load_dwordx4 v[36:39], v[36:37], off
	s_mov_b32 s27, s76
